# indexer K tiles 0-2 of the next unit prefetched after the attention loop into idle registers; scoring prologue moves them instead of loading
# speedup vs baseline: 1.0071x; 1.0005x over previous
.LBB0_405:
	s_or_b64 exec, exec, s[0:1]
	s_add_i32 s86, 0, 0x27090
	s_cmp_lg_u32 s86, -1
	s_cselect_b32 s0, s86, 0
	s_cselect_b32 s1, s5, 0
	v_mov_b32_e32 v2, s0
	v_mov_b32_e32 v3, s1
	s_waitcnt lgkmcnt(0)
	s_barrier
	flat_load_dword v1, v[2:3] sc0 sc1
	s_waitcnt vmcnt(0) lgkmcnt(0)
	v_readfirstlane_b32 s36, v1
	s_cmpk_gt_i32 s36, 0x803
	s_cbranch_scc1 .LBB0_799
	s_add_u32 s50, s18, 0x6300000
	s_addc_u32 s51, s19, 0
	s_add_u32 s0, s18, 0xe700000
	s_addc_u32 s1, s19, 0
	v_writelane_b32 v250, s0, 44
	v_ashrrev_i32_e32 v1, 6, v0
	v_and_b32_e32 v185, 3, v1
	v_writelane_b32 v250, s1, 45
	s_add_u32 s0, s18, 0xeb20000
	s_addc_u32 s1, s19, 0
	v_writelane_b32 v250, s0, 46
	v_lshlrev_b32_e32 v2, 10, v185
	v_and_b32_e32 v184, 63, v0
	v_writelane_b32 v250, s1, 47
	s_add_u32 s0, s18, 0x10d28000
	s_addc_u32 s1, s19, 0
	v_writelane_b32 v250, s0, 48
	v_lshlrev_b32_e32 v3, 3, v0
	v_and_b32_e32 v192, 0xffffffc0, v0
	v_writelane_b32 v250, s1, 49
	s_add_u32 s0, s18, 0x14f28000
	s_addc_u32 s1, s19, 0
	v_writelane_b32 v250, s0, 50
	s_add_i32 s17, 0, 0x23000
	v_lshlrev_b32_e32 v190, 3, v1
	v_writelane_b32 v250, s1, 51
	v_cmp_gt_u32_e64 s[0:1], 64, v0
	v_lshl_add_u32 v191, v1, 12, s17
	v_and_b32_e32 v3, 0xfffff800, v3
	v_writelane_b32 v250, s0, 36
	v_lshl_add_u32 v187, v185, 12, s17
	v_readlane_b32 s6, v251, 52
	v_writelane_b32 v250, s1, 37
	s_movk_i32 s1, 0x100
	v_readlane_b32 s0, v250, 20
	v_cmp_gt_u32_e64 s[40:41], s1, v0
	v_and_b32_e32 v0, 0xffffff00, v0
	v_add_u32_e32 v186, s0, v2
	s_mov_b32 s0, 0x8400
	v_mad_u32_u24 v189, v185, s0, 0
	s_movk_i32 s0, 0x4400
	v_mul_lo_u32 v1, v1, s0
	v_cmp_eq_u32_e64 s[0:1], s1, v0
	v_add_u32_e32 v193, 0, v1
	v_readlane_b32 s10, v251, 55
	v_writelane_b32 v250, s0, 52
	v_readlane_b32 s12, v251, 57
	v_add_u32_e32 v188, v187, v3
	v_writelane_b32 v250, s1, 53
	s_add_u32 s0, s18, 0x6300004
	v_writelane_b32 v250, s0, 54
	s_addc_u32 s0, s19, 0
	v_writelane_b32 v250, s0, 55
	s_add_u32 s0, s18, 0x6300008
	v_writelane_b32 v250, s0, 56
	s_addc_u32 s0, s19, 0
	v_writelane_b32 v250, s0, 57
	s_add_u32 s0, s18, 0x630000c
	v_writelane_b32 v250, s0, 58
	s_addc_u32 s0, s19, 0
	v_writelane_b32 v250, s0, 59
	v_add_u32_e32 v194, 0x11000, v193
	v_readlane_b32 s0, v250, 21
	v_readlane_b32 s7, v251, 53
	v_readlane_b32 s4, v251, 54
	v_add_u32_e32 v195, s0, v2
	v_readlane_b32 s11, v251, 56
	v_readlane_b32 s13, v251, 58
	v_readlane_b32 s14, v250, 2
	v_readlane_b32 s98, v250, 46
	v_readlane_b32 s99, v250, 47
	v_and_b32_e32 v222, 63, v171
	v_lshrrev_b32_e32 v223, 6, v171
	v_lshlrev_b32_e32 v222, 4, v222
	v_lshl_add_u32 v222, v223, 12, v222
	s_nop 1
	global_load_dwordx4 v[80:83], v222, s[98:99]
	global_load_dwordx4 v[84:87], v222, s[98:99] offset:1024
	global_load_dwordx4 v[88:91], v222, s[98:99] offset:2048
	global_load_dwordx4 v[92:95], v222, s[98:99] offset:3072
	s_add_u32 s98, s98, 0x8000
	s_addc_u32 s99, s99, 0
	global_load_dwordx4 v[206:209], v222, s[98:99]
	global_load_dwordx4 v[210:213], v222, s[98:99] offset:1024
	global_load_dwordx4 v[214:217], v222, s[98:99] offset:2048
	global_load_dwordx4 v[218:221], v222, s[98:99] offset:3072
	s_add_u32 s98, s98, 0x8000
	s_addc_u32 s99, s99, 0
	global_load_dwordx4 v[198:201], v222, s[98:99]
	global_load_dwordx4 v[244:247], v222, s[98:99] offset:1024
	global_load_dwordx4 v[160:163], v222, s[98:99] offset:2048
	global_load_dwordx4 v[176:179], v222, s[98:99] offset:3072
	s_branch .LBB0_408

.LBB0_412:
	s_or_b64 exec, exec, s[0:1]
	s_lshl_b32 s0, s36, 2
	s_sub_i32 s38, 0x200c, s0
	s_sub_i32 s80, 0x210c, s0
	s_cmpk_gt_u32 s80, 0xff
	s_cselect_b64 s[0:1], -1, 0
	s_lshr_b32 s81, s80, 8
	v_mov_b32_e32 v172, v184
	s_cmpk_lt_u32 s80, 0x100
	s_cbranch_scc1 .LBB0_439
	v_readlane_b32 s36, v250, 46
	s_ashr_i32 s39, s38, 31
	v_ashrrev_i32_e32 v0, 5, v172
	v_lshlrev_b32_e32 v168, 3, v172
	v_readlane_b32 s37, v250, 47
	s_lshl_b64 s[48:49], s[38:39], 14
	v_ashrrev_i32_e32 v1, 31, v0
	v_lshl_add_u64 v[96:97], v[168:169], 1, s[36:37]
	s_add_u32 s36, s50, s48
	s_addc_u32 s37, s51, s49
	v_lshlrev_b64 v[2:3], 1, v[0:1]
	v_lshl_add_u64 v[4:5], s[36:37], 0, v[2:3]
	s_or_b32 s36, s38, 1
	s_ashr_i32 s37, s36, 31
	s_lshl_b64 s[44:45], s[36:37], 14
	s_add_u32 s36, s50, s44
	s_addc_u32 s37, s51, s45
	v_lshl_add_u64 v[6:7], s[36:37], 0, v[2:3]
	s_or_b32 s36, s38, 2
	s_ashr_i32 s37, s36, 31
	s_lshl_b64 s[46:47], s[36:37], 14
	s_add_u32 s36, s50, s46
	s_addc_u32 s37, s51, s47
	v_lshl_add_u64 v[8:9], s[36:37], 0, v[2:3]
	s_or_b32 s36, s38, 3
	s_ashr_i32 s37, s36, 31
	s_lshl_b64 s[42:43], s[36:37], 14
	s_movk_i32 s15, 0x1000
	s_add_u32 s36, s50, s42
	v_add_co_u32_e32 v6, vcc, s15, v6
	s_addc_u32 s37, s51, s43
	s_nop 0
	v_addc_co_u32_e32 v7, vcc, 0, v7, vcc
	v_lshl_add_u64 v[10:11], s[36:37], 0, v[2:3]
	v_add_co_u32_e32 v10, vcc, s15, v10
	v_readlane_b32 s39, v250, 54
	s_nop 0
	v_addc_co_u32_e32 v11, vcc, 0, v11, vcc
	s_add_u32 s36, s39, s48
	v_readlane_b32 s58, v250, 55
	s_addc_u32 s37, s58, s49
	v_add_co_u32_e32 v4, vcc, s15, v4
	v_lshl_add_u64 v[12:13], s[36:37], 0, v[2:3]
	s_nop 0
	v_addc_co_u32_e32 v5, vcc, 0, v5, vcc
	s_add_u32 s36, s39, s44
	v_add_co_u32_e32 v12, vcc, s15, v12
	s_addc_u32 s37, s58, s45
	s_nop 0
	v_addc_co_u32_e32 v13, vcc, 0, v13, vcc
	v_lshl_add_u64 v[14:15], s[36:37], 0, v[2:3]
	v_add_co_u32_e32 v14, vcc, s15, v14
	s_add_u32 s36, s39, s46
	s_nop 0
	v_addc_co_u32_e32 v15, vcc, 0, v15, vcc
	s_addc_u32 s37, s58, s47
	v_add_co_u32_e32 v8, vcc, s15, v8
	v_lshl_add_u64 v[16:17], s[36:37], 0, v[2:3]
	s_nop 0
	v_addc_co_u32_e32 v9, vcc, 0, v9, vcc
	s_add_u32 s36, s39, s42
	v_add_co_u32_e32 v16, vcc, s15, v16
	s_addc_u32 s37, s58, s43
	v_readlane_b32 s39, v250, 56
	v_addc_co_u32_e32 v17, vcc, 0, v17, vcc
	v_lshl_add_u64 v[18:19], s[36:37], 0, v[2:3]
	s_add_u32 s36, s39, s48
	v_readlane_b32 s58, v250, 57
	v_add_co_u32_e32 v18, vcc, s15, v18
	s_addc_u32 s37, s58, s49
	s_nop 0
	v_addc_co_u32_e32 v19, vcc, 0, v19, vcc
	v_mov_b32_e32 v241, 0x1680
	s_add_u32 s100, s50, s48
	s_addc_u32 s101, s51, s49
	global_load_dwordx4 v[224:227], v241, s[100:101]
	s_add_u32 s100, s50, s44
	s_addc_u32 s101, s51, s45
	global_load_dwordx4 v[228:231], v241, s[100:101]
	s_add_u32 s100, s50, s46
	s_addc_u32 s101, s51, s47
	global_load_dwordx4 v[232:235], v241, s[100:101]
	s_add_u32 s100, s50, s42
	s_addc_u32 s101, s51, s43
	global_load_dwordx4 v[236:239], v241, s[100:101]
	v_lshl_add_u64 v[4:5], s[36:37], 0, v[2:3]
	s_add_u32 s36, s39, s44
	s_addc_u32 s37, s58, s45
	v_lshl_add_u64 v[6:7], s[36:37], 0, v[2:3]
	s_add_u32 s36, s39, s46
	s_addc_u32 s37, s58, s47
	v_lshl_add_u64 v[8:9], s[36:37], 0, v[2:3]
	s_add_u32 s36, s39, s42
	v_add_co_u32_e32 v6, vcc, s15, v6
	s_addc_u32 s37, s58, s43
	s_nop 0
	v_addc_co_u32_e32 v7, vcc, 0, v7, vcc
	v_lshl_add_u64 v[10:11], s[36:37], 0, v[2:3]
	v_add_co_u32_e32 v10, vcc, s15, v10
	v_readlane_b32 s39, v250, 58
	s_nop 0
	v_addc_co_u32_e32 v11, vcc, 0, v11, vcc
	s_add_u32 s36, s39, s48
	v_readlane_b32 s48, v250, 59
	s_addc_u32 s37, s48, s49
	v_add_co_u32_e32 v4, vcc, s15, v4
	v_lshl_add_u64 v[12:13], s[36:37], 0, v[2:3]
	s_nop 0
	v_addc_co_u32_e32 v5, vcc, 0, v5, vcc
	s_add_u32 s36, s39, s44
	v_add_co_u32_e32 v12, vcc, s15, v12
	s_addc_u32 s37, s48, s45
	s_nop 0
	v_addc_co_u32_e32 v13, vcc, 0, v13, vcc
	v_lshl_add_u64 v[14:15], s[36:37], 0, v[2:3]
	v_add_co_u32_e32 v14, vcc, s15, v14
	s_add_u32 s36, s39, s46
	s_nop 0
	v_addc_co_u32_e32 v15, vcc, 0, v15, vcc
	s_addc_u32 s37, s48, s47
	v_add_co_u32_e32 v8, vcc, s15, v8
	v_lshl_add_u64 v[16:17], s[36:37], 0, v[2:3]
	s_nop 0
	v_addc_co_u32_e32 v9, vcc, 0, v9, vcc
	s_add_u32 s36, s39, s42
	v_add_co_u32_e32 v16, vcc, s15, v16
	s_addc_u32 s37, s48, s43
	s_nop 0
	v_addc_co_u32_e32 v17, vcc, 0, v17, vcc
	v_lshl_add_u64 v[2:3], s[36:37], 0, v[2:3]
	v_add_co_u32_e32 v2, vcc, s15, v2
	v_and_or_b32 v168, v172, 3, s38
	s_nop 0
	v_addc_co_u32_e32 v3, vcc, 0, v3, vcc
	v_lshlrev_b64 v[2:3], 14, v[168:169]
	v_lshlrev_b32_e32 v4, 5, v172
	s_add_i32 s39, s81, 0x7ffffff
	v_lshl_add_u64 v[2:3], s[50:51], 0, v[2:3]
	v_and_b32_e32 v168, 0x380, v4
	v_lshlrev_b32_e32 v4, 3, v0
	v_lshl_add_u64 v[2:3], v[2:3], 0, v[168:169]
	v_ashrrev_i32_e32 v5, 31, v4
	s_lshl_b32 s44, s39, 5
	v_lshl_add_u64 v[2:3], v[4:5], 1, v[2:3]
	s_mov_b64 s[36:37], 0x1200
	s_cmpk_lt_u32 s80, 0x300
	v_lshl_add_u64 v[4:5], v[2:3], 0, s[36:37]
	s_cselect_b32 s36, s44, 64
	s_add_i32 s36, s36, s76
	s_or_b32 s42, s36, 3
	v_add_co_u32_e32 v2, vcc, s15, v2
	s_ashr_i32 s43, s42, 31
	s_nop 0
	v_addc_co_u32_e32 v3, vcc, 0, v3, vcc
	s_lshl_b64 s[42:43], s[42:43], 10
	global_load_dwordx4 v[16:19], v[4:5], off offset:64
	global_load_dwordx4 v[20:23], v[4:5], off offset:32
	global_load_dwordx4 v[24:27], v[4:5], off offset:96
	global_load_dwordx4 v[28:31], v[2:3], off offset:512
	v_lshl_add_u64 v[2:3], v[96:97], 0, s[42:43]
	s_or_b32 s42, s36, 2
	s_ashr_i32 s43, s42, 31
	s_lshl_b64 s[42:43], s[42:43], 10
	v_lshl_add_u64 v[4:5], v[96:97], 0, s[42:43]
	s_or_b32 s42, s36, 1
	s_ashr_i32 s43, s42, 31
	s_ashr_i32 s37, s36, 31
	s_lshl_b64 s[42:43], s[42:43], 10
	s_lshl_b64 s[36:37], s[36:37], 10
	s_cmpk_lt_u32 s80, 0x200
	v_lshl_add_u64 v[4:5], v[96:97], 0, s[36:37]
	s_cselect_b32 s36, s44, 32
	s_add_i32 s36, s36, s76
	v_lshl_add_u64 v[2:3], v[96:97], 0, s[42:43]
	s_or_b32 s42, s36, 3
	s_ashr_i32 s43, s42, 31
	s_lshl_b64 s[42:43], s[42:43], 10
	v_lshl_add_u64 v[2:3], v[96:97], 0, s[42:43]
	s_or_b32 s42, s36, 2
	s_ashr_i32 s43, s42, 31
	s_lshl_b64 s[42:43], s[42:43], 10
	v_lshl_add_u64 v[4:5], v[96:97], 0, s[42:43]
	s_or_b32 s42, s36, 1
	s_ashr_i32 s37, s36, 31
	s_ashr_i32 s43, s42, 31
	s_lshl_b64 s[36:37], s[36:37], 10
	s_lshl_b64 s[42:43], s[42:43], 10
	v_lshl_add_u64 v[4:5], v[96:97], 0, s[36:37]
	v_readlane_b32 s36, v251, 50
	v_lshl_add_u64 v[2:3], v[96:97], 0, s[42:43]
	v_readlane_b32 s37, v251, 51
	v_lshl_add_u64 v[2:3], v[96:97], 0, s[36:37]
	v_lshl_add_u64 v[4:5], v[96:97], 0, s[6:7]
	v_lshl_add_u64 v[2:3], v[96:97], 0, s[10:11]
	v_lshl_add_u64 v[4:5], v[96:97], 0, s[12:13]
	v_lshrrev_b32_e32 v240, 5, v172
	v_sub_u32_e32 v240, 1, v240
	v_lshlrev_b32_e32 v240, 4, v240
	s_waitcnt vmcnt(4)
	v_lshlrev_b32_e32 v242, v240, v224
	v_and_b32_e32 v98, 0xffff0000, v242
	v_lshlrev_b32_e32 v242, v240, v228
	v_and_b32_e32 v106, 0xffff0000, v242
	v_lshlrev_b32_e32 v242, v240, v232
	v_and_b32_e32 v100, 0xffff0000, v242
	v_lshlrev_b32_e32 v242, v240, v236
	v_and_b32_e32 v107, 0xffff0000, v242
	v_lshlrev_b32_e32 v242, v240, v225
	v_and_b32_e32 v99, 0xffff0000, v242
	v_lshlrev_b32_e32 v242, v240, v229
	v_and_b32_e32 v108, 0xffff0000, v242
	v_lshlrev_b32_e32 v242, v240, v233
	v_and_b32_e32 v101, 0xffff0000, v242
	v_lshlrev_b32_e32 v242, v240, v237
	v_and_b32_e32 v109, 0xffff0000, v242
	v_lshlrev_b32_e32 v242, v240, v226
	v_and_b32_e32 v102, 0xffff0000, v242
	v_lshlrev_b32_e32 v242, v240, v230
	v_and_b32_e32 v110, 0xffff0000, v242
	v_lshlrev_b32_e32 v242, v240, v234
	v_and_b32_e32 v104, 0xffff0000, v242
	v_lshlrev_b32_e32 v242, v240, v238
	v_and_b32_e32 v111, 0xffff0000, v242
	v_lshlrev_b32_e32 v242, v240, v227
	v_and_b32_e32 v103, 0xffff0000, v242
	v_lshlrev_b32_e32 v242, v240, v231
	v_and_b32_e32 v112, 0xffff0000, v242
	v_lshlrev_b32_e32 v242, v240, v235
	v_and_b32_e32 v105, 0xffff0000, v242
	v_lshlrev_b32_e32 v242, v240, v239
	v_and_b32_e32 v113, 0xffff0000, v242
	v_lshlrev_b32_e32 v1, 1, v0
	s_mov_b32 s36, 0x10800
	v_and_b32_e32 v2, 31, v172
	v_mul_lo_u32 v3, v0, s36
	v_lshl_add_u32 v115, v0, 13, s17
	v_or_b32_e32 v0, 1, v1
	v_add_u32_e32 v116, s38, v0
	v_lshl_add_u32 v117, v0, 12, s17
	v_lshl_or_b32 v0, v2, 2, v3
	v_add_u32_e32 v114, s38, v1
	v_add_u32_e32 v118, s4, v2
	v_add_u32_e32 v119, s14, v0
	s_waitcnt vmcnt(0)
	v_mov_b32_e32 v36, v80
	v_mov_b32_e32 v37, v81
	v_mov_b32_e32 v38, v82
	v_mov_b32_e32 v39, v83
	v_mov_b32_e32 v32, v84
	v_mov_b32_e32 v33, v85
	v_mov_b32_e32 v34, v86
	v_mov_b32_e32 v35, v87
	v_mov_b32_e32 v44, v88
	v_mov_b32_e32 v45, v89
	v_mov_b32_e32 v46, v90
	v_mov_b32_e32 v47, v91
	v_mov_b32_e32 v40, v92
	v_mov_b32_e32 v41, v93
	v_mov_b32_e32 v42, v94
	v_mov_b32_e32 v43, v95
	v_mov_b32_e32 v76, v206
	v_mov_b32_e32 v77, v207
	v_mov_b32_e32 v78, v208
	v_mov_b32_e32 v79, v209
	v_mov_b32_e32 v72, v210
	v_mov_b32_e32 v73, v211
	v_mov_b32_e32 v74, v212
	v_mov_b32_e32 v75, v213
	v_mov_b32_e32 v68, v214
	v_mov_b32_e32 v69, v215
	v_mov_b32_e32 v70, v216
	v_mov_b32_e32 v71, v217
	v_mov_b32_e32 v64, v218
	v_mov_b32_e32 v65, v219
	v_mov_b32_e32 v66, v220
	v_mov_b32_e32 v67, v221
	v_mov_b32_e32 v60, v198
	v_mov_b32_e32 v61, v199
	v_mov_b32_e32 v62, v200
	v_mov_b32_e32 v63, v201
	v_mov_b32_e32 v56, v244
	v_mov_b32_e32 v57, v245
	v_mov_b32_e32 v58, v246
	v_mov_b32_e32 v59, v247
	v_mov_b32_e32 v52, v160
	v_mov_b32_e32 v53, v161
	v_mov_b32_e32 v54, v162
	v_mov_b32_e32 v55, v163
	v_mov_b32_e32 v48, v176
	v_mov_b32_e32 v49, v177
	v_mov_b32_e32 v50, v178
	v_mov_b32_e32 v51, v179
	s_mov_b32 s46, 6
	s_branch .LBB0_416

.LBB0_513:
	s_or_b64 exec, exec, s[0:1]
	v_readlane_b32 s98, v250, 46
	v_readlane_b32 s99, v250, 47
	v_and_b32_e32 v222, 63, v171
	v_lshrrev_b32_e32 v223, 6, v171
	v_lshlrev_b32_e32 v222, 4, v222
	v_lshl_add_u32 v222, v223, 12, v222
	s_nop 1
	global_load_dwordx4 v[80:83], v222, s[98:99]
	global_load_dwordx4 v[84:87], v222, s[98:99] offset:1024
	global_load_dwordx4 v[88:91], v222, s[98:99] offset:2048
	global_load_dwordx4 v[92:95], v222, s[98:99] offset:3072
	s_add_u32 s98, s98, 0x8000
	s_addc_u32 s99, s99, 0
	global_load_dwordx4 v[206:209], v222, s[98:99]
	global_load_dwordx4 v[210:213], v222, s[98:99] offset:1024
	global_load_dwordx4 v[214:217], v222, s[98:99] offset:2048
	global_load_dwordx4 v[218:221], v222, s[98:99] offset:3072
	s_add_u32 s98, s98, 0x8000
	s_addc_u32 s99, s99, 0
	global_load_dwordx4 v[198:201], v222, s[98:99]
	global_load_dwordx4 v[244:247], v222, s[98:99] offset:1024
	global_load_dwordx4 v[160:163], v222, s[98:99] offset:2048
	global_load_dwordx4 v[176:179], v222, s[98:99] offset:3072
	s_mov_b64 s[0:1], exec
	v_readlane_b32 s36, v250, 52
	v_readlane_b32 s37, v250, 53
	s_and_b64 s[36:37], s[0:1], s[36:37]
	s_mov_b64 exec, s[36:37]
	s_cbranch_execz .LBB0_515
	v_lshl_add_u32 v64, v172, 2, v193
	ds_write2st64_b32 v64, v204, v164 offset1:1
	ds_write2st64_b32 v64, v60, v61 offset0:2 offset1:3
	ds_write2st64_b32 v64, v62, v63 offset0:4 offset1:5
	ds_write2st64_b32 v64, v56, v57 offset0:6 offset1:7
	ds_write2st64_b32 v64, v58, v59 offset0:8 offset1:9
	ds_write2st64_b32 v64, v52, v53 offset0:10 offset1:11
	ds_write2st64_b32 v64, v54, v55 offset0:12 offset1:13
	ds_write2st64_b32 v64, v48, v49 offset0:14 offset1:15
	ds_write2st64_b32 v64, v50, v51 offset0:16 offset1:17
	ds_write2st64_b32 v64, v44, v45 offset0:18 offset1:19
	ds_write2st64_b32 v64, v46, v47 offset0:20 offset1:21
	ds_write2st64_b32 v64, v40, v41 offset0:22 offset1:23
	ds_write2st64_b32 v64, v42, v43 offset0:24 offset1:25
	ds_write2st64_b32 v64, v36, v37 offset0:26 offset1:27
	ds_write2st64_b32 v64, v38, v39 offset0:28 offset1:29
	ds_write2st64_b32 v64, v32, v33 offset0:30 offset1:31
	ds_write2st64_b32 v64, v34, v35 offset0:32 offset1:33
	ds_write2st64_b32 v64, v28, v29 offset0:34 offset1:35
	ds_write2st64_b32 v64, v30, v31 offset0:36 offset1:37
	ds_write2st64_b32 v64, v24, v25 offset0:38 offset1:39
	ds_write2st64_b32 v64, v26, v27 offset0:40 offset1:41
	ds_write2st64_b32 v64, v20, v21 offset0:42 offset1:43
	ds_write2st64_b32 v64, v22, v23 offset0:44 offset1:45
	ds_write2st64_b32 v64, v16, v17 offset0:46 offset1:47
	ds_write2st64_b32 v64, v18, v19 offset0:48 offset1:49
	ds_write2st64_b32 v64, v12, v13 offset0:50 offset1:51
	ds_write2st64_b32 v64, v14, v15 offset0:52 offset1:53
	ds_write2st64_b32 v64, v8, v9 offset0:54 offset1:55
	ds_write2st64_b32 v64, v10, v11 offset0:56 offset1:57
	ds_write2st64_b32 v64, v4, v5 offset0:58 offset1:59
	ds_write2st64_b32 v64, v6, v7 offset0:60 offset1:61
	ds_write2st64_b32 v64, v0, v1 offset0:62 offset1:63
	ds_write2st64_b32 v64, v2, v3 offset0:64 offset1:65
.LBB0_515:
	s_or_b64 exec, exec, s[0:1]
	s_waitcnt lgkmcnt(0)
	s_barrier
	s_and_saveexec_b64 s[0:1], s[40:41]
	s_cbranch_execz .LBB0_517
	s_waitcnt vmcnt(12)
	v_lshl_add_u32 v67, v172, 2, v194
	ds_read2st64_b32 v[68:69], v67 offset1:1
	ds_read2st64_b32 v[96:97], v67 offset0:2 offset1:3
	ds_read2st64_b32 v[98:99], v67 offset0:4 offset1:5
	ds_read2st64_b32 v[100:101], v67 offset0:6 offset1:7
	ds_read2st64_b32 v[102:103], v67 offset0:8 offset1:9
	ds_read2st64_b32 v[104:105], v67 offset0:10 offset1:11
	ds_read2st64_b32 v[106:107], v67 offset0:12 offset1:13
	ds_read2st64_b32 v[108:109], v67 offset0:14 offset1:15
	ds_read2st64_b32 v[110:111], v67 offset0:16 offset1:17
	ds_read2st64_b32 v[112:113], v67 offset0:18 offset1:19
	ds_read2st64_b32 v[114:115], v67 offset0:20 offset1:21
	ds_read2st64_b32 v[116:117], v67 offset0:22 offset1:23
	ds_read2st64_b32 v[118:119], v67 offset0:24 offset1:25
	ds_read2st64_b32 v[120:121], v67 offset0:26 offset1:27
	ds_read2st64_b32 v[122:123], v67 offset0:28 offset1:29
	ds_read2st64_b32 v[124:125], v67 offset0:30 offset1:31
	ds_read2st64_b32 v[126:127], v67 offset0:32 offset1:33
	ds_read2st64_b32 v[128:129], v67 offset0:34 offset1:35
	ds_read2st64_b32 v[130:131], v67 offset0:36 offset1:37
	ds_read2st64_b32 v[132:133], v67 offset0:38 offset1:39
	ds_read2st64_b32 v[134:135], v67 offset0:40 offset1:41
	ds_read2st64_b32 v[136:137], v67 offset0:42 offset1:43
	ds_read2st64_b32 v[138:139], v67 offset0:44 offset1:45
	ds_read2st64_b32 v[140:141], v67 offset0:46 offset1:47
	ds_read2st64_b32 v[142:143], v67 offset0:48 offset1:49
	ds_read2st64_b32 v[144:145], v67 offset0:50 offset1:51
	ds_read2st64_b32 v[146:147], v67 offset0:52 offset1:53
	ds_read2st64_b32 v[148:149], v67 offset0:54 offset1:55
	ds_read2st64_b32 v[150:151], v67 offset0:56 offset1:57
	ds_read2st64_b32 v[152:153], v67 offset0:58 offset1:59
	ds_read2st64_b32 v[154:155], v67 offset0:60 offset1:61
	ds_read2st64_b32 v[156:157], v67 offset0:62 offset1:63
	ds_read2st64_b32 v[158:159], v67 offset0:64 offset1:65
	v_max_f32_e32 v70, v204, v204
	v_readlane_b32 s36, v250, 50
	v_readlane_b32 s37, v250, 51
	v_and_b32_e32 v75, 15, v172
	v_lshrrev_b32_e32 v76, 4, v172
	v_mul_u32_u24_e32 v75, 0x210, v75
	v_lshl_add_u32 v75, v76, 3, v75
	v_add_u32_e32 v75, v75, v193
	v_lshrrev_b32_e32 v76, 5, v172
	v_mul_u32_u24_e32 v76, 0x210, v76
	v_and_b32_e32 v77, 31, v172
	v_lshl_add_u32 v76, v77, 4, v76
	v_add_u32_e32 v76, v76, v193
	s_waitcnt lgkmcnt(0)
	v_max_f32_e32 v66, v68, v68
	v_max_f32_e32 v66, v70, v66
	v_sub_f32_e32 v70, v204, v66
	v_sub_f32_e32 v66, v68, v66
	v_exp_f32_e32 v70, v70
	v_exp_f32_e32 v71, v66
	v_mov_b32_e32 v165, v69
	v_lshl_add_u64 v[64:65], v[174:175], 1, s[36:37]
	v_lshlrev_b32_e32 v72, 4, v172
	v_mov_b32_e32 v73, 0
	v_pk_mul_f32 v[68:69], v[164:165], v[70:71]
	v_lshl_add_u64 v[64:65], v[64:65], 0, v[72:73]
	v_add_f32_e32 v66, v68, v69
	v_div_scale_f32 v68, s[36:37], v66, v66, 1.0
	v_rcp_f32_e32 v69, v68
	s_nop 0
	v_fma_f32 v72, -v68, v69, 1.0
	v_fmac_f32_e32 v69, v72, v69
	v_div_scale_f32 v72, vcc, 1.0, v66, 1.0
	v_mul_f32_e32 v73, v72, v69
	v_fma_f32 v74, -v68, v73, v72
	v_fmac_f32_e32 v73, v74, v69
	v_fma_f32 v68, -v68, v73, v72
	v_div_fmas_f32 v68, v68, v69, v73
	v_div_fixup_f32 v68, v68, v66, 1.0
	v_mul_f32_e32 v66, v70, v68
	v_mul_f32_e32 v68, v71, v68
	s_mov_b64 s[36:37], 0x1000
	v_lshl_add_u64 v[78:79], v[64:65], 0, s[36:37]
	v_pk_mul_f32 v[96:97], v[68:69], v[96:97] op_sel_hi:[0,1]
	v_pk_mul_f32 v[98:99], v[68:69], v[98:99] op_sel_hi:[0,1]
	v_pk_fma_f32 v[60:61], v[66:67], v[60:61], v[96:97] op_sel_hi:[0,1,1]
	v_pk_fma_f32 v[62:63], v[66:67], v[62:63], v[98:99] op_sel_hi:[0,1,1]
	v_cvt_pk_bf16_f32 v60, v60, v61
	v_cvt_pk_bf16_f32 v61, v62, v63
	ds_write_b64 v75, v[60:61]
	v_pk_mul_f32 v[100:101], v[68:69], v[100:101] op_sel_hi:[0,1]
	v_pk_mul_f32 v[102:103], v[68:69], v[102:103] op_sel_hi:[0,1]
	v_pk_fma_f32 v[56:57], v[66:67], v[56:57], v[100:101] op_sel_hi:[0,1,1]
	v_pk_fma_f32 v[58:59], v[66:67], v[58:59], v[102:103] op_sel_hi:[0,1,1]
	v_cvt_pk_bf16_f32 v56, v56, v57
	v_cvt_pk_bf16_f32 v57, v58, v59
	ds_write_b64 v75, v[56:57] offset:32
	v_pk_mul_f32 v[104:105], v[68:69], v[104:105] op_sel_hi:[0,1]
	v_pk_mul_f32 v[106:107], v[68:69], v[106:107] op_sel_hi:[0,1]
	v_pk_fma_f32 v[52:53], v[66:67], v[52:53], v[104:105] op_sel_hi:[0,1,1]
	v_pk_fma_f32 v[54:55], v[66:67], v[54:55], v[106:107] op_sel_hi:[0,1,1]
	v_cvt_pk_bf16_f32 v52, v52, v53
	v_cvt_pk_bf16_f32 v53, v54, v55
	ds_write_b64 v75, v[52:53] offset:64
	v_pk_mul_f32 v[108:109], v[68:69], v[108:109] op_sel_hi:[0,1]
	v_pk_mul_f32 v[110:111], v[68:69], v[110:111] op_sel_hi:[0,1]
	v_pk_fma_f32 v[48:49], v[66:67], v[48:49], v[108:109] op_sel_hi:[0,1,1]
	v_pk_fma_f32 v[50:51], v[66:67], v[50:51], v[110:111] op_sel_hi:[0,1,1]
	v_cvt_pk_bf16_f32 v48, v48, v49
	v_cvt_pk_bf16_f32 v49, v50, v51
	ds_write_b64 v75, v[48:49] offset:96
	v_pk_mul_f32 v[112:113], v[68:69], v[112:113] op_sel_hi:[0,1]
	v_pk_mul_f32 v[114:115], v[68:69], v[114:115] op_sel_hi:[0,1]
	v_pk_fma_f32 v[44:45], v[66:67], v[44:45], v[112:113] op_sel_hi:[0,1,1]
	v_pk_fma_f32 v[46:47], v[66:67], v[46:47], v[114:115] op_sel_hi:[0,1,1]
	v_cvt_pk_bf16_f32 v44, v44, v45
	v_cvt_pk_bf16_f32 v45, v46, v47
	ds_write_b64 v75, v[44:45] offset:128
	v_pk_mul_f32 v[116:117], v[68:69], v[116:117] op_sel_hi:[0,1]
	v_pk_mul_f32 v[118:119], v[68:69], v[118:119] op_sel_hi:[0,1]
	v_pk_fma_f32 v[40:41], v[66:67], v[40:41], v[116:117] op_sel_hi:[0,1,1]
	v_pk_fma_f32 v[42:43], v[66:67], v[42:43], v[118:119] op_sel_hi:[0,1,1]
	v_cvt_pk_bf16_f32 v40, v40, v41
	v_cvt_pk_bf16_f32 v41, v42, v43
	ds_write_b64 v75, v[40:41] offset:160
	v_pk_mul_f32 v[120:121], v[68:69], v[120:121] op_sel_hi:[0,1]
	v_pk_mul_f32 v[122:123], v[68:69], v[122:123] op_sel_hi:[0,1]
	v_pk_fma_f32 v[36:37], v[66:67], v[36:37], v[120:121] op_sel_hi:[0,1,1]
	v_pk_fma_f32 v[38:39], v[66:67], v[38:39], v[122:123] op_sel_hi:[0,1,1]
	v_cvt_pk_bf16_f32 v36, v36, v37
	v_cvt_pk_bf16_f32 v37, v38, v39
	ds_write_b64 v75, v[36:37] offset:192
	v_pk_mul_f32 v[124:125], v[68:69], v[124:125] op_sel_hi:[0,1]
	v_pk_mul_f32 v[126:127], v[68:69], v[126:127] op_sel_hi:[0,1]
	v_pk_fma_f32 v[32:33], v[66:67], v[32:33], v[124:125] op_sel_hi:[0,1,1]
	v_pk_fma_f32 v[34:35], v[66:67], v[34:35], v[126:127] op_sel_hi:[0,1,1]
	v_cvt_pk_bf16_f32 v32, v32, v33
	v_cvt_pk_bf16_f32 v33, v34, v35
	ds_write_b64 v75, v[32:33] offset:224
	v_pk_mul_f32 v[128:129], v[68:69], v[128:129] op_sel_hi:[0,1]
	v_pk_mul_f32 v[130:131], v[68:69], v[130:131] op_sel_hi:[0,1]
	v_pk_fma_f32 v[28:29], v[66:67], v[28:29], v[128:129] op_sel_hi:[0,1,1]
	v_pk_fma_f32 v[30:31], v[66:67], v[30:31], v[130:131] op_sel_hi:[0,1,1]
	v_cvt_pk_bf16_f32 v28, v28, v29
	v_cvt_pk_bf16_f32 v29, v30, v31
	ds_write_b64 v75, v[28:29] offset:256
	v_pk_mul_f32 v[132:133], v[68:69], v[132:133] op_sel_hi:[0,1]
	v_pk_mul_f32 v[134:135], v[68:69], v[134:135] op_sel_hi:[0,1]
	v_pk_fma_f32 v[24:25], v[66:67], v[24:25], v[132:133] op_sel_hi:[0,1,1]
	v_pk_fma_f32 v[26:27], v[66:67], v[26:27], v[134:135] op_sel_hi:[0,1,1]
	v_cvt_pk_bf16_f32 v24, v24, v25
	v_cvt_pk_bf16_f32 v25, v26, v27
	ds_write_b64 v75, v[24:25] offset:288
	v_pk_mul_f32 v[136:137], v[68:69], v[136:137] op_sel_hi:[0,1]
	v_pk_mul_f32 v[138:139], v[68:69], v[138:139] op_sel_hi:[0,1]
	v_pk_fma_f32 v[20:21], v[66:67], v[20:21], v[136:137] op_sel_hi:[0,1,1]
	v_pk_fma_f32 v[22:23], v[66:67], v[22:23], v[138:139] op_sel_hi:[0,1,1]
	v_cvt_pk_bf16_f32 v20, v20, v21
	v_cvt_pk_bf16_f32 v21, v22, v23
	ds_write_b64 v75, v[20:21] offset:320
	v_pk_mul_f32 v[140:141], v[68:69], v[140:141] op_sel_hi:[0,1]
	v_pk_mul_f32 v[142:143], v[68:69], v[142:143] op_sel_hi:[0,1]
	v_pk_fma_f32 v[16:17], v[66:67], v[16:17], v[140:141] op_sel_hi:[0,1,1]
	v_pk_fma_f32 v[18:19], v[66:67], v[18:19], v[142:143] op_sel_hi:[0,1,1]
	v_cvt_pk_bf16_f32 v16, v16, v17
	v_cvt_pk_bf16_f32 v17, v18, v19
	ds_write_b64 v75, v[16:17] offset:352
	v_pk_mul_f32 v[144:145], v[68:69], v[144:145] op_sel_hi:[0,1]
	v_pk_mul_f32 v[146:147], v[68:69], v[146:147] op_sel_hi:[0,1]
	v_pk_fma_f32 v[12:13], v[66:67], v[12:13], v[144:145] op_sel_hi:[0,1,1]
	v_pk_fma_f32 v[14:15], v[66:67], v[14:15], v[146:147] op_sel_hi:[0,1,1]
	v_cvt_pk_bf16_f32 v12, v12, v13
	v_cvt_pk_bf16_f32 v13, v14, v15
	ds_write_b64 v75, v[12:13] offset:384
	v_pk_mul_f32 v[148:149], v[68:69], v[148:149] op_sel_hi:[0,1]
	v_pk_mul_f32 v[150:151], v[68:69], v[150:151] op_sel_hi:[0,1]
	v_pk_fma_f32 v[8:9], v[66:67], v[8:9], v[148:149] op_sel_hi:[0,1,1]
	v_pk_fma_f32 v[10:11], v[66:67], v[10:11], v[150:151] op_sel_hi:[0,1,1]
	v_cvt_pk_bf16_f32 v8, v8, v9
	v_cvt_pk_bf16_f32 v9, v10, v11
	ds_write_b64 v75, v[8:9] offset:416
	v_pk_mul_f32 v[152:153], v[68:69], v[152:153] op_sel_hi:[0,1]
	v_pk_mul_f32 v[154:155], v[68:69], v[154:155] op_sel_hi:[0,1]
	v_pk_fma_f32 v[4:5], v[66:67], v[4:5], v[152:153] op_sel_hi:[0,1,1]
	v_pk_fma_f32 v[6:7], v[66:67], v[6:7], v[154:155] op_sel_hi:[0,1,1]
	v_cvt_pk_bf16_f32 v4, v4, v5
	v_cvt_pk_bf16_f32 v5, v6, v7
	ds_write_b64 v75, v[4:5] offset:448
	v_pk_mul_f32 v[156:157], v[68:69], v[156:157] op_sel_hi:[0,1]
	v_pk_mul_f32 v[158:159], v[68:69], v[158:159] op_sel_hi:[0,1]
	v_pk_fma_f32 v[0:1], v[66:67], v[0:1], v[156:157] op_sel_hi:[0,1,1]
	v_pk_fma_f32 v[2:3], v[66:67], v[2:3], v[158:159] op_sel_hi:[0,1,1]
	v_cvt_pk_bf16_f32 v0, v0, v1
	v_cvt_pk_bf16_f32 v1, v2, v3
	ds_write_b64 v75, v[0:1] offset:480
	s_waitcnt lgkmcnt(0)
	ds_read_b128 v[96:99], v76
	ds_read_b128 v[100:103], v76 offset:1056
	ds_read_b128 v[104:107], v76 offset:2112
	ds_read_b128 v[108:111], v76 offset:3168
	ds_read_b128 v[112:115], v76 offset:4224
	ds_read_b128 v[116:119], v76 offset:5280
	ds_read_b128 v[120:123], v76 offset:6336
	ds_read_b128 v[124:127], v76 offset:7392
	s_waitcnt lgkmcnt(7)
	global_store_dwordx4 v[64:65], v[96:99], off
	s_waitcnt lgkmcnt(6)
	global_store_dwordx4 v[64:65], v[100:103], off offset:1024
	s_waitcnt lgkmcnt(5)
	global_store_dwordx4 v[64:65], v[104:107], off offset:2048
	s_waitcnt lgkmcnt(4)
	global_store_dwordx4 v[64:65], v[108:111], off offset:3072
	s_waitcnt lgkmcnt(3)
	global_store_dwordx4 v[78:79], v[112:115], off
	s_waitcnt lgkmcnt(2)
	global_store_dwordx4 v[78:79], v[116:119], off offset:1024
	s_waitcnt lgkmcnt(1)
	global_store_dwordx4 v[78:79], v[120:123], off offset:2048
	s_waitcnt lgkmcnt(0)
	global_store_dwordx4 v[78:79], v[124:127], off offset:3072

.LBB0_799:
	s_waitcnt vmcnt(0)
	s_add_u32 s0, s18, 0xfca8000
	s_addc_u32 s1, s19, 0
	v_readlane_b32 s4, v250, 30
	s_add_u32 s36, s18, 0x24128000
	v_readlane_b32 s5, v250, 31
	s_addc_u32 s37, s19, 0
	s_lshl_b64 s[38:39], s[4:5], 12
	s_mov_b64 s[40:41], s[18:19]
	v_readlane_b32 s4, v252, 19
	v_readlane_b32 s8, v252, 23
	v_readlane_b32 s9, v252, 24
	s_add_u32 s38, s8, s38
	v_readlane_b32 s10, v252, 25
	v_readlane_b32 s11, v252, 26
	s_addc_u32 s39, s9, s39
	v_readlane_b32 s4, v250, 29
	s_mov_b64 s[10:11], s[40:41]
	s_cmpk_gt_i32 s4, 0x7f
	v_readlane_b32 s5, v252, 20
	v_readlane_b32 s6, v252, 21
	v_readlane_b32 s7, v252, 22
	v_readlane_b32 s12, v252, 27
	v_readlane_b32 s13, v252, 28
	v_readlane_b32 s14, v252, 29
	v_readlane_b32 s15, v252, 30
	v_readlane_b32 s16, v252, 31
	v_readlane_b32 s17, v252, 32
	v_readlane_b32 s18, v252, 33
	v_readlane_b32 s19, v252, 34
	s_cbranch_scc1 .LBB0_806
	s_add_u32 s48, s10, 0xec28000
	v_readlane_b32 s58, v250, 29
	s_addc_u32 s49, s11, 0
	s_lshl_b32 s40, s58, 8
	v_readlane_b32 s4, v250, 32
	s_or_b32 s50, s40, 0xb0
	s_lshl_b32 s51, s4, 8
	s_branch .LBB0_802
